# scan->gate as XCD-local seam, reworked: per-batch 'past gdn_pre' and 'past scan' words in the group-indexed blocks (no overlap with the per-XCC words), all arrivals posted at seam entry, deferred laun
# speedup vs baseline: 1.0045x; 1.0045x over previous
.LBB0_308:
	s_waitcnt vmcnt(0)
	v_readfirstlane_b32 s4, v194
	s_cmp_gt_u32 s4, 63
	v_readlane_b32 s77, v242, 9
	v_readlane_b32 s78, v241, 13
	v_readlane_b32 s40, v241, 12
	v_readlane_b32 s41, v241, 4
	s_barrier
	s_cbranch_scc1 .LBB0_362
	v_mbcnt_lo_u32_b32 v0, -1, 0
	v_mbcnt_hi_u32_b32 v0, -1, v0
	s_nop 0
	v_cmp_eq_u32_e32 vcc, 0, v0
	s_and_saveexec_b64 s[6:7], vcc
	s_cbranch_execz .LBB0_361
	v_mov_b32_e32 v0, 0x23ff0
	s_waitcnt vmcnt(0) lgkmcnt(0)
	ds_read_b128 v[0:3], v0
	s_waitcnt lgkmcnt(0)
	v_readfirstlane_b32 s8, v2
	s_nop 0
	s_cmp_eq_u32 s8, 0
	s_cbranch_scc1 .Lfb_slow_1
	v_readfirstlane_b32 s9, v0
	s_cmp_eq_u32 s9, 32
	s_cbranch_scc0 .Lfb_xcd_1
	buffer_inv sc1
	s_getreg_b32 s8, hwreg(HW_REG_XCC_ID, 0, 4)
	s_and_b32 s8, s8, 7
	s_lshl_b32 s8, s8, 8
	s_add_u32 s8, s8, 0x3600
	s_add_u32 s4, s92, 0x510000
	s_addc_u32 s5, s93, 0
	v_mov_b32_e32 v7, 1
	s_bfe_u32 s9, s2, 0x20006
	s_lshl_b32 s9, s9, 2
	s_add_u32 s9, s9, s8
	s_add_u32 s9, s9, 0xe0
	v_mov_b32_e32 v6, s9
	global_atomic_add v6, v7, s[4:5]
	s_and_b32 s9, s2, 7
	s_lshl_b32 s9, s9, 8
	s_add_u32 s9, s9, 0x3604
	v_mov_b32_e32 v6, s9
	global_atomic_add v6, v7, s[4:5]
	s_bfe_u32 s9, s2, 0x20006
	s_lshl_b32 s9, s9, 2
	s_add_u32 s9, s9, s8
	s_add_u32 s9, s9, 0xe0
	v_mov_b32_e32 v6, s9
	s_mov_b32 s9, 0

.Lfb_xcd_1:
	s_add_u32 s4, s92, 0x510000
	s_addc_u32 s5, s93, 0
	s_and_b32 s9, s2, 7
	s_lshl_b32 s9, s9, 8
	s_add_u32 s9, s9, 0x3604
	v_mov_b32_e32 v6, s9
	v_mov_b32_e32 v7, 1
	global_atomic_add v6, v7, s[4:5]
	buffer_inv sc1
	v_add_u32_e32 v3, 1, v3
	v_mov_b32_e32 v4, 0x23ffc
	ds_write_b32 v4, v3
	v_mul_lo_u32 v5, v3, v0
	s_getreg_b32 s8, hwreg(HW_REG_XCC_ID, 0, 4)
	s_and_b32 s8, s8, 7
	s_lshl_b32 s8, s8, 8
	s_add_u32 s8, s8, 0x3680
	s_add_u32 s4, s92, 0x510000
	s_addc_u32 s5, s93, 0
	v_mov_b32_e32 v6, s8
	v_mov_b32_e32 v7, 1
	global_atomic_add v6, v7, s[4:5]
	s_mov_b32 s9, 0

.Lscan_loop:
	s_and_b32 s7, s6, 3
	s_lshl_b32 s7, s7, 12
	v_add_u32_e32 v23, s7, v22
	ds_read_b128 v[32:35], v10 offset:0
	ds_read_b128 v[48:51], v11 offset:0
	ds_read_b128 v[36:39], v10 offset:64
	ds_read_b128 v[52:55], v12 offset:0
	ds_read_b128 v[40:43], v10 offset:128
	ds_read_b128 v[56:59], v13 offset:0
	ds_read_b128 v[44:47], v10 offset:192
	ds_read_b128 v[60:63], v14 offset:0
	ds_read_u16 v80, v23 offset:0
	ds_read_u16 v81, v23 offset:64
	ds_read_u16 v82, v23 offset:128
	ds_read_u16 v83, v23 offset:192
	s_add_u32 s33, s6, 1
	s_min_u32 s33, s33, 31
	s_add_u32 s36, s6, 2
	s_min_u32 s36, s36, 31
	v_readlane_b32 s37, v24, s6
	s_nop 1
	v_mul_f32_e32 v92, s37, v92
	v_mul_f32_e32 v93, s37, v93
	v_mul_f32_e32 v94, s37, v94
	v_mul_f32_e32 v95, s37, v95
	v_mul_f32_e32 v96, s37, v96
	v_mul_f32_e32 v97, s37, v97
	v_mul_f32_e32 v98, s37, v98
	v_mul_f32_e32 v99, s37, v99
	s_waitcnt lgkmcnt(10)
	v_mfma_f32_16x16x32_bf16 v[84:87], v[48:51], v[32:35], 0
	s_waitcnt lgkmcnt(8)
	v_mfma_f32_16x16x32_bf16 v[84:87], v[52:55], v[36:39], v[84:87]
	s_waitcnt lgkmcnt(6)
	v_mfma_f32_16x16x32_bf16 v[84:87], v[56:59], v[40:43], v[84:87]
	s_waitcnt lgkmcnt(4)
	v_mfma_f32_16x16x32_bf16 v[84:87], v[60:63], v[44:47], v[84:87]
	ds_read_b128 v[64:67], v11 offset:32768
	ds_read_b128 v[68:71], v12 offset:32768
	ds_read_b128 v[72:75], v13 offset:32768
	ds_read_b128 v[76:79], v14 offset:32768
	s_waitcnt lgkmcnt(4)
	v_lshlrev_b32_e32 v80, 16, v80
	v_lshlrev_b32_e32 v81, 16, v81
	v_lshlrev_b32_e32 v82, 16, v82
	v_lshlrev_b32_e32 v83, 16, v83
	v_sub_f32_e32 v26, v80, v84
	v_sub_f32_e32 v27, v81, v85
	v_sub_f32_e32 v28, v82, v86
	v_sub_f32_e32 v29, v83, v87
	v_cvt_pk_bf16_f32 v26, v26, v27
	v_cvt_pk_bf16_f32 v27, v28, v29
	ds_write_b64 v20, v[26:27]
	s_lshl_b32 s7, s33, 14
	s_add_u32 s26, s14, s7
	s_addc_u32 s27, s15, 0
	s_add_i32 m0, s30, 0x14000
	s_nop 0
	global_load_lds_dwordx4 v5, s[26:27]
	s_add_i32 m0, s30, 0x14400
	s_nop 0
	global_load_lds_dwordx4 v6, s[26:27]
	s_lshl_b32 s7, s33, 13
	s_add_u32 s28, s18, s7
	s_addc_u32 s29, s19, 0
	s_add_i32 m0, s31, 0x1a000
	s_nop 0
	global_load_lds_dwordx4 v7, s[28:29]
	s_lshl_b32 s7, s36, 14
	s_add_u32 s26, s24, s7
	s_addc_u32 s27, s25, 0
	s_add_u32 s8, s6, 2
	s_and_b32 s8, s8, 3
	s_lshl_b32 s8, s8, 12
	s_add_u32 s8, s8, s32
	s_add_i32 m0, s8, 0x1f400
	s_nop 0
	global_load_lds_dwordx4 v8, s[26:27]
	s_waitcnt vmcnt(10) lgkmcnt(0)
	s_barrier
	ds_read_b128 v[100:103], v19
	ds_read_b128 v[108:111], v15 offset:0
	ds_read_b128 v[112:115], v15 offset:2048
	ds_read_b128 v[104:107], v19 offset:64
	ds_read_b128 v[116:119], v16 offset:0
	ds_read_b128 v[120:123], v16 offset:2048
	ds_read_b128 v[124:127], v17 offset:0
	ds_read_b128 v[128:131], v18 offset:0
	v_mfma_f32_16x16x32_bf16 v[88:91], v[32:35], v[64:67], 0
	v_mfma_f32_16x16x32_bf16 v[88:91], v[36:39], v[68:71], v[88:91]
	v_mfma_f32_16x16x32_bf16 v[88:91], v[40:43], v[72:75], v[88:91]
	v_mfma_f32_16x16x32_bf16 v[88:91], v[44:47], v[76:79], v[88:91]
	s_waitcnt lgkmcnt(6)
	v_mfma_f32_16x16x32_bf16 v[92:95], v[108:111], v[100:103], v[92:95]
	s_waitcnt lgkmcnt(5)
	v_mfma_f32_16x16x32_bf16 v[96:99], v[112:115], v[100:103], v[96:99]
	s_waitcnt lgkmcnt(3)
	v_mfma_f32_16x16x32_bf16 v[92:95], v[116:119], v[104:107], v[92:95]
	s_waitcnt lgkmcnt(2)
	v_mfma_f32_16x16x32_bf16 v[96:99], v[120:123], v[104:107], v[96:99]
	s_waitcnt lgkmcnt(1)
	v_mfma_f32_16x16x32_bf16 v[88:91], v[100:103], v[124:127], v[88:91]
	s_waitcnt lgkmcnt(0)
	v_mfma_f32_16x16x32_bf16 v[88:91], v[104:107], v[128:131], v[88:91]
	s_lshl_b32 s7, s6, 14
	s_add_u32 s28, s24, s7
	s_addc_u32 s29, s25, 0
	s_nop 1
	v_cvt_pk_bf16_f32 v26, v92, v93
	v_cvt_pk_bf16_f32 v27, v94, v95
	v_cvt_pk_bf16_f32 v28, v96, v97
	v_cvt_pk_bf16_f32 v29, v98, v99
	ds_write_b64 v21, v[26:27]
	ds_write_b64 v21, v[28:29] offset:32
	s_lshl_b32 s7, s36, 14
	s_add_u32 s26, s10, s7
	s_addc_u32 s27, s11, 0
	s_add_i32 m0, s30, 0x0
	s_nop 0
	global_load_lds_dwordx4 v3, s[26:27]
	s_add_i32 m0, s30, 0x400
	s_nop 0
	global_load_lds_dwordx4 v4, s[26:27]
	s_lshl_b32 s7, s36, 14
	s_add_u32 s26, s12, s7
	s_addc_u32 s27, s13, 0
	s_add_i32 m0, s30, 0x8000
	s_nop 0
	global_load_lds_dwordx4 v3, s[26:27]
	s_add_i32 m0, s30, 0x8400
	s_nop 0
	global_load_lds_dwordx4 v4, s[26:27]
	v_cvt_pk_bf16_f32 v80, v88, v89
	v_cvt_pk_bf16_f32 v81, v90, v91
	global_store_dwordx2 v9, v[80:81], s[28:29]
	s_add_u32 s6, s6, 1
	s_waitcnt vmcnt(10) lgkmcnt(0)
	s_barrier
	s_and_b32 s7, s6, 3
	s_lshl_b32 s7, s7, 12
	v_add_u32_e32 v23, s7, v22
	ds_read_b128 v[32:35], v10 offset:0
	ds_read_b128 v[48:51], v11 offset:16384
	ds_read_b128 v[36:39], v10 offset:64
	ds_read_b128 v[52:55], v12 offset:16384
	ds_read_b128 v[40:43], v10 offset:128
	ds_read_b128 v[56:59], v13 offset:16384
	ds_read_b128 v[44:47], v10 offset:192
	ds_read_b128 v[60:63], v14 offset:16384
	ds_read_u16 v80, v23 offset:0
	ds_read_u16 v81, v23 offset:64
	ds_read_u16 v82, v23 offset:128
	ds_read_u16 v83, v23 offset:192
	s_add_u32 s33, s6, 1
	s_min_u32 s33, s33, 31
	s_add_u32 s36, s6, 2
	s_min_u32 s36, s36, 31
	v_readlane_b32 s37, v24, s6
	s_nop 1
	v_mul_f32_e32 v92, s37, v92
	v_mul_f32_e32 v93, s37, v93
	v_mul_f32_e32 v94, s37, v94
	v_mul_f32_e32 v95, s37, v95
	v_mul_f32_e32 v96, s37, v96
	v_mul_f32_e32 v97, s37, v97
	v_mul_f32_e32 v98, s37, v98
	v_mul_f32_e32 v99, s37, v99
	s_waitcnt lgkmcnt(10)
	v_mfma_f32_16x16x32_bf16 v[84:87], v[48:51], v[32:35], 0
	s_waitcnt lgkmcnt(8)
	v_mfma_f32_16x16x32_bf16 v[84:87], v[52:55], v[36:39], v[84:87]
	s_waitcnt lgkmcnt(6)
	v_mfma_f32_16x16x32_bf16 v[84:87], v[56:59], v[40:43], v[84:87]
	s_waitcnt lgkmcnt(4)
	v_mfma_f32_16x16x32_bf16 v[84:87], v[60:63], v[44:47], v[84:87]
	ds_read_b128 v[64:67], v11 offset:49152
	ds_read_b128 v[68:71], v12 offset:49152
	ds_read_b128 v[72:75], v13 offset:49152
	ds_read_b128 v[76:79], v14 offset:49152
	s_waitcnt lgkmcnt(4)
	v_lshlrev_b32_e32 v80, 16, v80
	v_lshlrev_b32_e32 v81, 16, v81
	v_lshlrev_b32_e32 v82, 16, v82
	v_lshlrev_b32_e32 v83, 16, v83
	v_sub_f32_e32 v26, v80, v84
	v_sub_f32_e32 v27, v81, v85
	v_sub_f32_e32 v28, v82, v86
	v_sub_f32_e32 v29, v83, v87
	v_cvt_pk_bf16_f32 v26, v26, v27
	v_cvt_pk_bf16_f32 v27, v28, v29
	ds_write_b64 v20, v[26:27]
	s_lshl_b32 s7, s33, 14
	s_add_u32 s26, s14, s7
	s_addc_u32 s27, s15, 0
	s_add_i32 m0, s30, 0x10000
	s_nop 0
	global_load_lds_dwordx4 v5, s[26:27]
	s_add_i32 m0, s30, 0x10400
	s_nop 0
	global_load_lds_dwordx4 v6, s[26:27]
	s_lshl_b32 s7, s33, 13
	s_add_u32 s28, s18, s7
	s_addc_u32 s29, s19, 0
	s_add_i32 m0, s31, 0x18000
	s_nop 0
	global_load_lds_dwordx4 v7, s[28:29]
	s_lshl_b32 s7, s36, 14
	s_add_u32 s26, s24, s7
	s_addc_u32 s27, s25, 0
	s_add_u32 s8, s6, 2
	s_and_b32 s8, s8, 3
	s_lshl_b32 s8, s8, 12
	s_add_u32 s8, s8, s32
	s_add_i32 m0, s8, 0x1f400
	s_nop 0
	global_load_lds_dwordx4 v8, s[26:27]
	s_waitcnt vmcnt(10) lgkmcnt(0)
	s_barrier
	ds_read_b128 v[100:103], v19
	ds_read_b128 v[108:111], v15 offset:16384
	ds_read_b128 v[112:115], v15 offset:18432
	ds_read_b128 v[104:107], v19 offset:64
	ds_read_b128 v[116:119], v16 offset:16384
	ds_read_b128 v[120:123], v16 offset:18432
	ds_read_b128 v[124:127], v17 offset:8192
	ds_read_b128 v[128:131], v18 offset:8192
	v_mfma_f32_16x16x32_bf16 v[88:91], v[32:35], v[64:67], 0
	v_mfma_f32_16x16x32_bf16 v[88:91], v[36:39], v[68:71], v[88:91]
	v_mfma_f32_16x16x32_bf16 v[88:91], v[40:43], v[72:75], v[88:91]
	v_mfma_f32_16x16x32_bf16 v[88:91], v[44:47], v[76:79], v[88:91]
	s_waitcnt lgkmcnt(6)
	v_mfma_f32_16x16x32_bf16 v[92:95], v[108:111], v[100:103], v[92:95]
	s_waitcnt lgkmcnt(5)
	v_mfma_f32_16x16x32_bf16 v[96:99], v[112:115], v[100:103], v[96:99]
	s_waitcnt lgkmcnt(3)
	v_mfma_f32_16x16x32_bf16 v[92:95], v[116:119], v[104:107], v[92:95]
	s_waitcnt lgkmcnt(2)
	v_mfma_f32_16x16x32_bf16 v[96:99], v[120:123], v[104:107], v[96:99]
	s_waitcnt lgkmcnt(1)
	v_mfma_f32_16x16x32_bf16 v[88:91], v[100:103], v[124:127], v[88:91]
	s_waitcnt lgkmcnt(0)
	v_mfma_f32_16x16x32_bf16 v[88:91], v[104:107], v[128:131], v[88:91]
	s_lshl_b32 s7, s6, 14
	s_add_u32 s28, s24, s7
	s_addc_u32 s29, s25, 0
	s_nop 1
	v_cvt_pk_bf16_f32 v26, v92, v93
	v_cvt_pk_bf16_f32 v27, v94, v95
	v_cvt_pk_bf16_f32 v28, v96, v97
	v_cvt_pk_bf16_f32 v29, v98, v99
	ds_write_b64 v21, v[26:27]
	ds_write_b64 v21, v[28:29] offset:32
	s_lshl_b32 s7, s36, 14
	s_add_u32 s26, s10, s7
	s_addc_u32 s27, s11, 0
	s_add_i32 m0, s30, 0x4000
	s_nop 0
	global_load_lds_dwordx4 v3, s[26:27]
	s_add_i32 m0, s30, 0x4400
	s_nop 0
	global_load_lds_dwordx4 v4, s[26:27]
	s_lshl_b32 s7, s36, 14
	s_add_u32 s26, s12, s7
	s_addc_u32 s27, s13, 0
	s_add_i32 m0, s30, 0xc000
	s_nop 0
	global_load_lds_dwordx4 v3, s[26:27]
	s_add_i32 m0, s30, 0xc400
	s_nop 0
	global_load_lds_dwordx4 v4, s[26:27]
	v_cvt_pk_bf16_f32 v80, v88, v89
	v_cvt_pk_bf16_f32 v81, v90, v91
	global_store_dwordx2 v9, v[80:81], s[28:29]
	s_add_u32 s6, s6, 1
	s_waitcnt vmcnt(10) lgkmcnt(0)
	s_barrier
	s_cmp_lt_u32 s6, 32
	s_cbranch_scc1 .Lscan_loop
	s_lshl_b32 s56, s77, 5
	s_and_b32 s57, s40, 3
	s_lshl_b32 s72, s40, 5
	s_waitcnt vmcnt(0)
	v_readfirstlane_b32 s3, v194
	s_cmp_gt_u32 s3, 63
	s_barrier
	s_cbranch_scc1 .LBB0_421
	s_waitcnt vmcnt(2)
	v_mbcnt_lo_u32_b32 v0, -1, 0
	v_mbcnt_hi_u32_b32 v0, -1, v0
	s_nop 0
	v_cmp_eq_u32_e32 vcc, 0, v0
	s_and_saveexec_b64 s[6:7], vcc
	s_cbranch_execz .LBB0_420
	v_mov_b32_e32 v0, 0x23ff0
	s_waitcnt vmcnt(0) lgkmcnt(0)
	ds_read_b128 v[0:3], v0
	s_waitcnt lgkmcnt(0)
	v_readfirstlane_b32 s3, v2
	s_nop 0
	s_cmp_eq_u32 s3, 0
	s_cbranch_scc1 .Lfb_slow_2
	v_readfirstlane_b32 s8, v0
	s_cmp_eq_u32 s8, 32
	s_cbranch_scc0 .Lfb_xcd_2
	buffer_inv sc1
	s_getreg_b32 s3, hwreg(HW_REG_XCC_ID, 0, 4)
	s_and_b32 s3, s3, 7
	s_lshl_b32 s3, s3, 8
	s_add_u32 s3, s3, 0x3600
	s_add_u32 s4, s92, 0x510000
	s_addc_u32 s5, s93, 0
	v_mov_b32_e32 v7, 1
	s_mov_b32 s8, s3
	s_add_u32 s8, s8, 0x5c
	v_mov_b32_e32 v6, s8
	global_atomic_add v6, v7, s[4:5]
	s_and_b32 s8, s2, 7
	s_lshl_b32 s8, s8, 8
	s_add_u32 s8, s8, 0x3608
	v_mov_b32_e32 v6, s8
	global_atomic_add v6, v7, s[4:5]
	s_mov_b32 s8, s3
	s_add_u32 s8, s8, 0x5c
	v_mov_b32_e32 v6, s8
	s_and_b32 s8, s2, 7
	s_mul_i32 s8, s8, 11
	s_lshr_b32 s8, s8, 5
	s_lshl_b32 s8, s8, 8
	s_add_u32 s8, s8, 0x3604
	v_mov_b32_e32 v4, s8
	s_mov_b32 s8, 0

.Lfb_xcd_2:
	s_add_u32 s4, s92, 0x510000
	s_addc_u32 s5, s93, 0
	s_and_b32 s8, s2, 7
	s_lshl_b32 s8, s8, 8
	s_add_u32 s8, s8, 0x3608
	v_mov_b32_e32 v6, s8
	v_mov_b32_e32 v7, 1
	global_atomic_add v6, v7, s[4:5]
	s_and_b32 s8, s2, 7
	s_mul_i32 s8, s8, 11
	s_lshr_b32 s8, s8, 5
	s_lshl_b32 s8, s8, 8
	s_add_u32 s8, s8, 0x3604
	v_mov_b32_e32 v6, s8
	s_mov_b32 s8, 0

.Lfb_slow_2:
	s_add_u32 s4, s92, 0x510000
	s_addc_u32 s5, s93, 0
	s_and_b32 s8, s2, 7
	s_lshl_b32 s8, s8, 8
	s_add_u32 s8, s8, 0x3608
	v_mov_b32_e32 v6, s8
	v_mov_b32_e32 v7, 1
	global_atomic_add v6, v7, s[4:5]
	s_add_i32 s3, 0, 0x23ff0
	v_mov_b32_e32 v0, s3
	s_waitcnt vmcnt(0) expcnt(0) lgkmcnt(0)
	ds_read_b32 v2, v0
	s_add_i32 s3, 0, 0x23ff4
	v_mov_b32_e32 v0, s3
	ds_read_b32 v0, v0
	s_waitcnt lgkmcnt(1)
	v_cmp_ne_u32_e32 vcc, 0, v2
	s_cbranch_vccnz .LBB0_384
	s_mov_b32 s3, 1
	v_mov_b32_e32 v16, 0
	s_branch .LBB0_372

.LBB0_424:
	v_readfirstlane_b32 s4, v194
	s_cmp_gt_u32 s4, 63
	s_cbranch_scc1 .Lgc_skip
	s_add_u32 s4, s92, 0x510000
	s_addc_u32 s5, s93, 0
	v_mov_b32_e32 v0, 0x3608
	s_mov_b32 s8, 0
.Lgc_spin:
	global_load_dword v18, v0, s[4:5] offset:0 sc1
	global_load_dword v19, v0, s[4:5] offset:256 sc1
	global_load_dword v20, v0, s[4:5] offset:512 sc1
	global_load_dword v21, v0, s[4:5] offset:768 sc1
	global_load_dword v22, v0, s[4:5] offset:1024 sc1
	global_load_dword v23, v0, s[4:5] offset:1280 sc1
	global_load_dword v24, v0, s[4:5] offset:1536 sc1
	global_load_dword v25, v0, s[4:5] offset:1792 sc1
	s_waitcnt vmcnt(0)
	v_min_u32_e32 v18, v18, v19
	v_min_u32_e32 v18, v18, v20
	v_min_u32_e32 v18, v18, v21
	v_min_u32_e32 v18, v18, v22
	v_min_u32_e32 v18, v18, v23
	v_min_u32_e32 v18, v18, v24
	v_min_u32_e32 v18, v18, v25
	v_readfirstlane_b32 s9, v18
	s_cmp_ge_u32 s9, 32
	s_cbranch_scc1 .Lgc_skip
	s_sleep 1
	s_add_u32 s8, s8, 1
	s_cmp_lt_u32 s8, 0x40000
	s_cbranch_scc1 .Lgc_spin
